# in-projection main loop peeled the same way (zero fill kept only on the quarter-unit path)
# baseline (speedup 1.0000x reference)
.LBB0_365:
	v_mov_b64_e32 v[2:3], 0x30c
	v_cmp_lt_i64_e32 vcc, s[2:3], v[2:3]
	s_lshl_b32 s2, s18, 8
	s_or_b32 s2, s2, 1
	s_cmp_lt_i32 s18, 64
	s_cselect_b32 s2, s2, 0x4003
	s_ashr_i32 s3, s2, 31
	s_lshl_b64 s[2:3], s[2:3], 11
	v_readlane_b32 s12, v252, 20
	v_readlane_b32 s13, v252, 21
	s_add_u32 s52, s12, s2
	s_addc_u32 s53, s13, s3
	s_and_b64 s[2:3], vcc, exec
	s_cselect_b32 s15, s53, s1
	s_cselect_b32 s19, s52, s0
	s_ashr_i32 s51, s50, 31
	s_lshl_b64 s[2:3], s[50:51], 19
	s_add_u32 s48, s23, s2
	s_addc_u32 s49, s34, s3
	s_and_b64 s[2:3], vcc, exec
	s_cselect_b32 s43, s49, s17
	s_cselect_b32 s44, s48, s16
	s_add_u32 s0, s0, 0x40080
	s_addc_u32 s1, s1, 0
	s_add_u32 s45, s16, 0x100
	v_mov_b32_e32 v2, 0
	s_addc_u32 s46, s17, 0
	s_mov_b32 s47, -2
	s_cmp_lg_u32 s98, 15
	s_cbranch_scc1 .Lq_unit
	s_add_u32 s2, s0, 0xfffc0080
	s_addc_u32 s3, s1, -1
	s_add_i32 s12, 0, 0x10000
	v_add_u32_e32 v142, s12, v227
	ds_read_b128 v[130:133], v142
	ds_read_b128 v[134:137], v142 offset:1024
	ds_read_b128 v[138:141], v142 offset:2048
	ds_read_b128 v[142:145], v142 offset:3072
	s_cmp_eq_u32 s47, 12
	s_cselect_b32 s17, s15, s3
	s_cselect_b32 s16, s19, s2
	s_cselect_b32 s3, s43, s46
	s_cselect_b32 s2, s44, s45
	v_lshl_add_u64 v[190:191], s[0:1], 0, v[162:163]
	s_add_i32 m0, s54, 0xc000
	ds_read_b128 v[146:149], v233
	ds_read_b128 v[150:153], v233 offset:1024
	ds_read_b128 v[166:169], v233 offset:2048
	ds_read_b128 v[170:173], v233 offset:3072
	ds_read_b128 v[174:177], v233 offset:4096
	ds_read_b128 v[178:181], v233 offset:5120
	ds_read_b128 v[182:185], v233 offset:6144
	ds_read_b128 v[186:189], v233 offset:7168
	global_load_lds_dwordx4 v[190:191], off
	v_lshl_add_u64 v[190:191], s[0:1], 0, v[164:165]
	s_add_i32 m0, s54, 0xe000
	s_nop 0
	global_load_lds_dwordx4 v[190:191], off
	s_waitcnt lgkmcnt(8)
	s_barrier
	s_waitcnt lgkmcnt(0)
	s_waitcnt lgkmcnt(0)
	s_nop 0
	v_mfma_f32_16x16x32_bf16 v[126:129], v[130:133], v[146:149], 0
	v_mfma_f32_16x16x32_bf16 v[122:125], v[138:141], v[146:149], 0
	v_mfma_f32_16x16x32_bf16 v[118:121], v[130:133], v[166:169], 0
	v_mfma_f32_16x16x32_bf16 v[114:117], v[138:141], v[166:169], 0
	v_mfma_f32_16x16x32_bf16 v[110:113], v[130:133], v[174:177], 0
	v_mfma_f32_16x16x32_bf16 v[106:109], v[138:141], v[174:177], 0
	v_mfma_f32_16x16x32_bf16 v[102:105], v[130:133], v[182:185], 0
	v_mfma_f32_16x16x32_bf16 v[98:101], v[138:141], v[182:185], 0
	v_mfma_f32_16x16x32_bf16 v[126:129], v[134:137], v[150:153], v[126:129]
	v_mfma_f32_16x16x32_bf16 v[122:125], v[142:145], v[150:153], v[122:125]
	v_mfma_f32_16x16x32_bf16 v[118:121], v[134:137], v[170:173], v[118:121]
	v_mfma_f32_16x16x32_bf16 v[114:117], v[142:145], v[170:173], v[114:117]
	v_mfma_f32_16x16x32_bf16 v[110:113], v[134:137], v[178:181], v[110:113]
	v_mfma_f32_16x16x32_bf16 v[106:109], v[142:145], v[178:181], v[106:109]
	v_mfma_f32_16x16x32_bf16 v[102:105], v[134:137], v[186:189], v[102:105]
	v_mfma_f32_16x16x32_bf16 v[98:101], v[142:145], v[186:189], v[98:101]
	s_barrier
	s_add_i32 s13, 0, 0x14000
	s_add_i32 s12, s12, s35
	v_add_u32_e32 v234, s13, v227
	v_lshl_add_u64 v[242:243], s[2:3], 0, v[0:1]
	s_mov_b32 m0, s12
	ds_read_b128 v[190:193], v234
	ds_read_b128 v[194:197], v234 offset:1024
	ds_read_b128 v[198:201], v234 offset:2048
	ds_read_b128 v[234:237], v234 offset:3072
	global_load_lds_dwordx4 v[242:243], off
	v_lshl_add_u64 v[244:245], s[2:3], 0, v[154:155]
	s_add_i32 m0, s12, 0x2000
	s_nop 0
	global_load_lds_dwordx4 v[244:245], off
	s_barrier
	s_waitcnt lgkmcnt(0)
	s_waitcnt lgkmcnt(0)
	v_mfma_f32_16x16x32_bf16 v[62:65], v[190:193], v[146:149], 0
	v_mfma_f32_16x16x32_bf16 v[58:61], v[198:201], v[146:149], 0
	v_mfma_f32_16x16x32_bf16 v[54:57], v[190:193], v[166:169], 0
	v_mfma_f32_16x16x32_bf16 v[50:53], v[198:201], v[166:169], 0
	v_mfma_f32_16x16x32_bf16 v[46:49], v[190:193], v[174:177], 0
	v_mfma_f32_16x16x32_bf16 v[42:45], v[198:201], v[174:177], 0
	v_mfma_f32_16x16x32_bf16 v[38:41], v[190:193], v[182:185], 0
	v_mfma_f32_16x16x32_bf16 v[34:37], v[198:201], v[182:185], 0
	v_mfma_f32_16x16x32_bf16 v[62:65], v[194:197], v[150:153], v[62:65]
	v_mfma_f32_16x16x32_bf16 v[58:61], v[234:237], v[150:153], v[58:61]
	v_mfma_f32_16x16x32_bf16 v[54:57], v[194:197], v[170:173], v[54:57]
	v_mfma_f32_16x16x32_bf16 v[50:53], v[234:237], v[170:173], v[50:53]
	v_mfma_f32_16x16x32_bf16 v[46:49], v[194:197], v[178:181], v[46:49]
	v_mfma_f32_16x16x32_bf16 v[42:45], v[234:237], v[178:181], v[42:45]
	v_mfma_f32_16x16x32_bf16 v[38:41], v[194:197], v[186:189], v[38:41]
	v_mfma_f32_16x16x32_bf16 v[34:37], v[234:237], v[186:189], v[34:37]
	s_mov_b32 m0, s54
	s_nop 0
	s_barrier
	ds_read_b128 v[146:149], v233 offset:16384
	ds_read_b128 v[150:153], v233 offset:17408
	ds_read_b128 v[166:169], v233 offset:18432
	ds_read_b128 v[170:173], v233 offset:19456
	ds_read_b128 v[174:177], v233 offset:20480
	ds_read_b128 v[178:181], v233 offset:21504
	ds_read_b128 v[182:185], v233 offset:22528
	ds_read_b128 v[186:189], v233 offset:23552
	global_load_lds_dwordx4 v250, s[16:17]
	s_nop 0
	s_mov_b32 m0, s55
	s_nop 0
	global_load_lds_dwordx4 v251, s[16:17]
	s_barrier
	s_waitcnt lgkmcnt(0)
	s_waitcnt lgkmcnt(0)
	s_nop 0
	v_mfma_f32_16x16x32_bf16 v[94:97], v[130:133], v[146:149], 0
	v_mfma_f32_16x16x32_bf16 v[90:93], v[138:141], v[146:149], 0
	v_mfma_f32_16x16x32_bf16 v[86:89], v[130:133], v[166:169], 0
	v_mfma_f32_16x16x32_bf16 v[82:85], v[138:141], v[166:169], 0
	v_mfma_f32_16x16x32_bf16 v[78:81], v[130:133], v[174:177], 0
	v_mfma_f32_16x16x32_bf16 v[74:77], v[138:141], v[174:177], 0
	v_mfma_f32_16x16x32_bf16 v[70:73], v[130:133], v[182:185], 0
	v_mfma_f32_16x16x32_bf16 v[66:69], v[138:141], v[182:185], 0
	v_mfma_f32_16x16x32_bf16 v[94:97], v[134:137], v[150:153], v[94:97]
	v_mfma_f32_16x16x32_bf16 v[90:93], v[142:145], v[150:153], v[90:93]
	v_mfma_f32_16x16x32_bf16 v[86:89], v[134:137], v[170:173], v[86:89]
	v_mfma_f32_16x16x32_bf16 v[82:85], v[142:145], v[170:173], v[82:85]
	v_mfma_f32_16x16x32_bf16 v[78:81], v[134:137], v[178:181], v[78:81]
	v_mfma_f32_16x16x32_bf16 v[74:77], v[142:145], v[178:181], v[74:77]
	v_mfma_f32_16x16x32_bf16 v[70:73], v[134:137], v[186:189], v[70:73]
	v_mfma_f32_16x16x32_bf16 v[66:69], v[142:145], v[186:189], v[66:69]
	s_barrier
	s_add_u32 s78, s2, 0x40000
	s_addc_u32 s79, s3, 0
	s_add_i32 s12, s13, s35
	v_lshl_add_u64 v[130:131], s[78:79], 0, v[0:1]
	s_mov_b32 m0, s12
	s_nop 0
	global_load_lds_dwordx4 v[130:131], off
	v_lshl_add_u64 v[130:131], s[78:79], 0, v[154:155]
	s_add_i32 m0, s12, 0x2000
	s_nop 0
	global_load_lds_dwordx4 v[130:131], off
	s_waitcnt vmcnt(6)
	s_barrier
	v_mfma_f32_16x16x32_bf16 v[30:33], v[190:193], v[146:149], 0
	v_mfma_f32_16x16x32_bf16 v[26:29], v[198:201], v[146:149], 0
	v_mfma_f32_16x16x32_bf16 v[22:25], v[190:193], v[166:169], 0
	v_mfma_f32_16x16x32_bf16 v[18:21], v[198:201], v[166:169], 0
	v_mfma_f32_16x16x32_bf16 v[14:17], v[190:193], v[174:177], 0
	v_mfma_f32_16x16x32_bf16 v[10:13], v[198:201], v[174:177], 0
	v_mfma_f32_16x16x32_bf16 v[6:9], v[190:193], v[182:185], 0
	v_mfma_f32_16x16x32_bf16 v[2:5], v[198:201], v[182:185], 0
	v_mfma_f32_16x16x32_bf16 v[30:33], v[194:197], v[150:153], v[30:33]
	v_mfma_f32_16x16x32_bf16 v[26:29], v[234:237], v[150:153], v[26:29]
	v_mfma_f32_16x16x32_bf16 v[22:25], v[194:197], v[170:173], v[22:25]
	v_mfma_f32_16x16x32_bf16 v[18:21], v[234:237], v[170:173], v[18:21]
	v_mfma_f32_16x16x32_bf16 v[14:17], v[194:197], v[178:181], v[14:17]
	v_mfma_f32_16x16x32_bf16 v[10:13], v[234:237], v[178:181], v[10:13]
	v_mfma_f32_16x16x32_bf16 v[6:9], v[194:197], v[186:189], v[6:9]
	v_mfma_f32_16x16x32_bf16 v[2:5], v[234:237], v[186:189], v[2:5]
	s_add_i32 s12, 0, 0x18000
	v_add_u32_e32 v142, s12, v227
	s_barrier
	ds_read_b128 v[130:133], v142
	ds_read_b128 v[134:137], v142 offset:1024
	ds_read_b128 v[138:141], v142 offset:2048
	ds_read_b128 v[142:145], v142 offset:3072
	s_add_u32 s16, s16, 0x40000
	s_addc_u32 s17, s17, 0
	s_mov_b32 m0, s58
	s_nop 0
	ds_read_b128 v[146:149], v233 offset:32768
	ds_read_b128 v[150:153], v233 offset:33792
	ds_read_b128 v[166:169], v233 offset:34816
	ds_read_b128 v[170:173], v233 offset:35840
	ds_read_b128 v[174:177], v233 offset:36864
	ds_read_b128 v[178:181], v233 offset:37888
	ds_read_b128 v[182:185], v233 offset:38912
	ds_read_b128 v[186:189], v233 offset:39936
	global_load_lds_dwordx4 v250, s[16:17]
	s_nop 0
	s_mov_b32 m0, s59
	s_nop 0
	global_load_lds_dwordx4 v251, s[16:17]
	s_waitcnt lgkmcnt(8)
	s_barrier
	s_waitcnt lgkmcnt(0)
	s_waitcnt lgkmcnt(0)
	v_mfma_f32_16x16x32_bf16 v[126:129], v[130:133], v[146:149], v[126:129]
	v_mfma_f32_16x16x32_bf16 v[122:125], v[138:141], v[146:149], v[122:125]
	v_mfma_f32_16x16x32_bf16 v[118:121], v[130:133], v[166:169], v[118:121]
	v_mfma_f32_16x16x32_bf16 v[114:117], v[138:141], v[166:169], v[114:117]
	v_mfma_f32_16x16x32_bf16 v[110:113], v[130:133], v[174:177], v[110:113]
	v_mfma_f32_16x16x32_bf16 v[106:109], v[138:141], v[174:177], v[106:109]
	v_mfma_f32_16x16x32_bf16 v[102:105], v[130:133], v[182:185], v[102:105]
	v_mfma_f32_16x16x32_bf16 v[98:101], v[138:141], v[182:185], v[98:101]
	v_mfma_f32_16x16x32_bf16 v[126:129], v[134:137], v[150:153], v[126:129]
	v_mfma_f32_16x16x32_bf16 v[122:125], v[142:145], v[150:153], v[122:125]
	v_mfma_f32_16x16x32_bf16 v[118:121], v[134:137], v[170:173], v[118:121]
	v_mfma_f32_16x16x32_bf16 v[114:117], v[142:145], v[170:173], v[114:117]
	v_mfma_f32_16x16x32_bf16 v[110:113], v[134:137], v[178:181], v[110:113]
	v_mfma_f32_16x16x32_bf16 v[106:109], v[142:145], v[178:181], v[106:109]
	v_mfma_f32_16x16x32_bf16 v[102:105], v[134:137], v[186:189], v[102:105]
	v_mfma_f32_16x16x32_bf16 v[98:101], v[142:145], v[186:189], v[98:101]
	s_barrier
	s_add_i32 s13, 0, 0x1c000
	s_add_i32 s12, s12, s35
	v_add_u32_e32 v234, s13, v227
	v_lshl_add_u64 v[242:243], v[242:243], 0, s[20:21]
	s_mov_b32 m0, s12
	ds_read_b128 v[190:193], v234
	ds_read_b128 v[194:197], v234 offset:1024
	ds_read_b128 v[198:201], v234 offset:2048
	ds_read_b128 v[234:237], v234 offset:3072
	global_load_lds_dwordx4 v[242:243], off
	v_lshl_add_u64 v[242:243], v[244:245], 0, s[20:21]
	s_add_i32 m0, s12, 0x2000
	s_nop 0
	global_load_lds_dwordx4 v[242:243], off
	s_barrier
	s_waitcnt lgkmcnt(0)
	s_waitcnt lgkmcnt(0)
	v_mfma_f32_16x16x32_bf16 v[62:65], v[190:193], v[146:149], v[62:65]
	v_mfma_f32_16x16x32_bf16 v[58:61], v[198:201], v[146:149], v[58:61]
	v_mfma_f32_16x16x32_bf16 v[54:57], v[190:193], v[166:169], v[54:57]
	v_mfma_f32_16x16x32_bf16 v[50:53], v[198:201], v[166:169], v[50:53]
	v_mfma_f32_16x16x32_bf16 v[46:49], v[190:193], v[174:177], v[46:49]
	v_mfma_f32_16x16x32_bf16 v[42:45], v[198:201], v[174:177], v[42:45]
	v_mfma_f32_16x16x32_bf16 v[38:41], v[190:193], v[182:185], v[38:41]
	v_mfma_f32_16x16x32_bf16 v[34:37], v[198:201], v[182:185], v[34:37]
	v_mfma_f32_16x16x32_bf16 v[62:65], v[194:197], v[150:153], v[62:65]
	v_mfma_f32_16x16x32_bf16 v[58:61], v[234:237], v[150:153], v[58:61]
	v_mfma_f32_16x16x32_bf16 v[54:57], v[194:197], v[170:173], v[54:57]
	v_mfma_f32_16x16x32_bf16 v[50:53], v[234:237], v[170:173], v[50:53]
	v_mfma_f32_16x16x32_bf16 v[46:49], v[194:197], v[178:181], v[46:49]
	v_mfma_f32_16x16x32_bf16 v[42:45], v[234:237], v[178:181], v[42:45]
	v_mfma_f32_16x16x32_bf16 v[38:41], v[194:197], v[186:189], v[38:41]
	v_mfma_f32_16x16x32_bf16 v[34:37], v[234:237], v[186:189], v[34:37]
	s_mov_b32 m0, s96
	s_add_u32 s78, s16, 0xfffc0080
	s_addc_u32 s79, s17, -1
	s_barrier
	ds_read_b128 v[146:149], v233 offset:49152
	ds_read_b128 v[150:153], v233 offset:50176
	ds_read_b128 v[166:169], v233 offset:51200
	ds_read_b128 v[170:173], v233 offset:52224
	ds_read_b128 v[174:177], v233 offset:53248
	ds_read_b128 v[178:181], v233 offset:54272
	ds_read_b128 v[182:185], v233 offset:55296
	ds_read_b128 v[186:189], v233 offset:56320
	global_load_lds_dwordx4 v250, s[78:79]
	s_nop 0
	s_mov_b32 m0, s97
	s_nop 0
	global_load_lds_dwordx4 v251, s[78:79]
	s_barrier
	s_waitcnt lgkmcnt(0)
	s_waitcnt lgkmcnt(0)
	s_nop 0
	v_mfma_f32_16x16x32_bf16 v[94:97], v[130:133], v[146:149], v[94:97]
	v_mfma_f32_16x16x32_bf16 v[90:93], v[138:141], v[146:149], v[90:93]
	v_mfma_f32_16x16x32_bf16 v[86:89], v[130:133], v[166:169], v[86:89]
	v_mfma_f32_16x16x32_bf16 v[82:85], v[138:141], v[166:169], v[82:85]
	v_mfma_f32_16x16x32_bf16 v[78:81], v[130:133], v[174:177], v[78:81]
	v_mfma_f32_16x16x32_bf16 v[74:77], v[138:141], v[174:177], v[74:77]
	v_mfma_f32_16x16x32_bf16 v[70:73], v[130:133], v[182:185], v[70:73]
	v_mfma_f32_16x16x32_bf16 v[66:69], v[138:141], v[182:185], v[66:69]
	v_mfma_f32_16x16x32_bf16 v[94:97], v[134:137], v[150:153], v[94:97]
	v_mfma_f32_16x16x32_bf16 v[90:93], v[142:145], v[150:153], v[90:93]
	v_mfma_f32_16x16x32_bf16 v[86:89], v[134:137], v[170:173], v[86:89]
	v_mfma_f32_16x16x32_bf16 v[82:85], v[142:145], v[170:173], v[82:85]
	v_mfma_f32_16x16x32_bf16 v[78:81], v[134:137], v[178:181], v[78:81]
	v_mfma_f32_16x16x32_bf16 v[74:77], v[142:145], v[178:181], v[74:77]
	v_mfma_f32_16x16x32_bf16 v[70:73], v[134:137], v[186:189], v[70:73]
	v_mfma_f32_16x16x32_bf16 v[66:69], v[142:145], v[186:189], v[66:69]
	s_barrier
	s_add_u32 s2, s2, 0x40080
	s_addc_u32 s3, s3, 0
	s_add_i32 s12, s13, s35
	v_lshl_add_u64 v[130:131], s[2:3], 0, v[0:1]
	s_mov_b32 m0, s12
	s_nop 0
	global_load_lds_dwordx4 v[130:131], off
	v_lshl_add_u64 v[130:131], s[2:3], 0, v[154:155]
	s_add_i32 m0, s12, 0x2000
	s_nop 0
	global_load_lds_dwordx4 v[130:131], off
	s_waitcnt vmcnt(6)
	s_barrier
	v_mfma_f32_16x16x32_bf16 v[30:33], v[190:193], v[146:149], v[30:33]
	v_mfma_f32_16x16x32_bf16 v[26:29], v[198:201], v[146:149], v[26:29]
	v_mfma_f32_16x16x32_bf16 v[22:25], v[190:193], v[166:169], v[22:25]
	v_mfma_f32_16x16x32_bf16 v[18:21], v[198:201], v[166:169], v[18:21]
	v_mfma_f32_16x16x32_bf16 v[14:17], v[190:193], v[174:177], v[14:17]
	v_mfma_f32_16x16x32_bf16 v[10:13], v[198:201], v[174:177], v[10:13]
	v_mfma_f32_16x16x32_bf16 v[6:9], v[190:193], v[182:185], v[6:9]
	v_mfma_f32_16x16x32_bf16 v[2:5], v[198:201], v[182:185], v[2:5]
	v_mfma_f32_16x16x32_bf16 v[30:33], v[194:197], v[150:153], v[30:33]
	v_mfma_f32_16x16x32_bf16 v[26:29], v[234:237], v[150:153], v[26:29]
	v_mfma_f32_16x16x32_bf16 v[22:25], v[194:197], v[170:173], v[22:25]
	v_mfma_f32_16x16x32_bf16 v[18:21], v[234:237], v[170:173], v[18:21]
	v_mfma_f32_16x16x32_bf16 v[14:17], v[194:197], v[178:181], v[14:17]
	v_mfma_f32_16x16x32_bf16 v[10:13], v[234:237], v[178:181], v[10:13]
	v_mfma_f32_16x16x32_bf16 v[6:9], v[194:197], v[186:189], v[6:9]
	v_mfma_f32_16x16x32_bf16 v[2:5], v[234:237], v[186:189], v[2:5]
	s_add_i32 s47, s47, 2
	s_add_u32 s0, s0, 0x100
	s_addc_u32 s1, s1, 0
	s_add_u32 s45, s45, 0x100
	s_addc_u32 s46, s46, 0
	s_cmp_gt_u32 s47, 13
	s_barrier
	s_cbranch_scc1 .Lpeel_x_366
.LBB0_366:
	s_add_u32 s2, s0, 0xfffc0080
	s_addc_u32 s3, s1, -1
	s_add_i32 s12, 0, 0x10000
	v_add_u32_e32 v142, s12, v227
	ds_read_b128 v[130:133], v142
	ds_read_b128 v[134:137], v142 offset:1024
	ds_read_b128 v[138:141], v142 offset:2048
	ds_read_b128 v[142:145], v142 offset:3072
	s_cmp_eq_u32 s47, 12
	s_cselect_b32 s17, s15, s3
	s_cselect_b32 s16, s19, s2
	s_cselect_b32 s3, s43, s46
	s_cselect_b32 s2, s44, s45
	v_lshl_add_u64 v[190:191], s[0:1], 0, v[162:163]
	s_add_i32 m0, s54, 0xc000
	ds_read_b128 v[146:149], v233
	ds_read_b128 v[150:153], v233 offset:1024
	ds_read_b128 v[166:169], v233 offset:2048
	ds_read_b128 v[170:173], v233 offset:3072
	ds_read_b128 v[174:177], v233 offset:4096
	ds_read_b128 v[178:181], v233 offset:5120
	ds_read_b128 v[182:185], v233 offset:6144
	ds_read_b128 v[186:189], v233 offset:7168
	global_load_lds_dwordx4 v[190:191], off
	v_lshl_add_u64 v[190:191], s[0:1], 0, v[164:165]
	s_add_i32 m0, s54, 0xe000
	s_nop 0
	global_load_lds_dwordx4 v[190:191], off
	s_waitcnt lgkmcnt(8)
	s_barrier
	s_waitcnt lgkmcnt(0)
	s_waitcnt lgkmcnt(0)
	v_mfma_f32_16x16x32_bf16 v[126:129], v[130:133], v[146:149], v[126:129]
	v_mfma_f32_16x16x32_bf16 v[122:125], v[138:141], v[146:149], v[122:125]
	v_mfma_f32_16x16x32_bf16 v[118:121], v[130:133], v[166:169], v[118:121]
	v_mfma_f32_16x16x32_bf16 v[114:117], v[138:141], v[166:169], v[114:117]
	v_mfma_f32_16x16x32_bf16 v[110:113], v[130:133], v[174:177], v[110:113]
	v_mfma_f32_16x16x32_bf16 v[106:109], v[138:141], v[174:177], v[106:109]
	v_mfma_f32_16x16x32_bf16 v[102:105], v[130:133], v[182:185], v[102:105]
	v_mfma_f32_16x16x32_bf16 v[98:101], v[138:141], v[182:185], v[98:101]
	v_mfma_f32_16x16x32_bf16 v[126:129], v[134:137], v[150:153], v[126:129]
	v_mfma_f32_16x16x32_bf16 v[122:125], v[142:145], v[150:153], v[122:125]
	v_mfma_f32_16x16x32_bf16 v[118:121], v[134:137], v[170:173], v[118:121]
	v_mfma_f32_16x16x32_bf16 v[114:117], v[142:145], v[170:173], v[114:117]
	v_mfma_f32_16x16x32_bf16 v[110:113], v[134:137], v[178:181], v[110:113]
	v_mfma_f32_16x16x32_bf16 v[106:109], v[142:145], v[178:181], v[106:109]
	v_mfma_f32_16x16x32_bf16 v[102:105], v[134:137], v[186:189], v[102:105]
	v_mfma_f32_16x16x32_bf16 v[98:101], v[142:145], v[186:189], v[98:101]
	s_barrier
	s_add_i32 s13, 0, 0x14000
	s_add_i32 s12, s12, s35
	v_add_u32_e32 v234, s13, v227
	v_lshl_add_u64 v[242:243], s[2:3], 0, v[0:1]
	s_mov_b32 m0, s12
	ds_read_b128 v[190:193], v234
	ds_read_b128 v[194:197], v234 offset:1024
	ds_read_b128 v[198:201], v234 offset:2048
	ds_read_b128 v[234:237], v234 offset:3072
	global_load_lds_dwordx4 v[242:243], off
	v_lshl_add_u64 v[244:245], s[2:3], 0, v[154:155]
	s_add_i32 m0, s12, 0x2000
	s_nop 0
	global_load_lds_dwordx4 v[244:245], off
	s_barrier
	s_waitcnt lgkmcnt(0)
	s_waitcnt lgkmcnt(0)
	v_mfma_f32_16x16x32_bf16 v[62:65], v[190:193], v[146:149], v[62:65]
	v_mfma_f32_16x16x32_bf16 v[58:61], v[198:201], v[146:149], v[58:61]
	v_mfma_f32_16x16x32_bf16 v[54:57], v[190:193], v[166:169], v[54:57]
	v_mfma_f32_16x16x32_bf16 v[50:53], v[198:201], v[166:169], v[50:53]
	v_mfma_f32_16x16x32_bf16 v[46:49], v[190:193], v[174:177], v[46:49]
	v_mfma_f32_16x16x32_bf16 v[42:45], v[198:201], v[174:177], v[42:45]
	v_mfma_f32_16x16x32_bf16 v[38:41], v[190:193], v[182:185], v[38:41]
	v_mfma_f32_16x16x32_bf16 v[34:37], v[198:201], v[182:185], v[34:37]
	v_mfma_f32_16x16x32_bf16 v[62:65], v[194:197], v[150:153], v[62:65]
	v_mfma_f32_16x16x32_bf16 v[58:61], v[234:237], v[150:153], v[58:61]
	v_mfma_f32_16x16x32_bf16 v[54:57], v[194:197], v[170:173], v[54:57]
	v_mfma_f32_16x16x32_bf16 v[50:53], v[234:237], v[170:173], v[50:53]
	v_mfma_f32_16x16x32_bf16 v[46:49], v[194:197], v[178:181], v[46:49]
	v_mfma_f32_16x16x32_bf16 v[42:45], v[234:237], v[178:181], v[42:45]
	v_mfma_f32_16x16x32_bf16 v[38:41], v[194:197], v[186:189], v[38:41]
	v_mfma_f32_16x16x32_bf16 v[34:37], v[234:237], v[186:189], v[34:37]
	s_mov_b32 m0, s54
	s_nop 0
	s_barrier
	ds_read_b128 v[146:149], v233 offset:16384
	ds_read_b128 v[150:153], v233 offset:17408
	ds_read_b128 v[166:169], v233 offset:18432
	ds_read_b128 v[170:173], v233 offset:19456
	ds_read_b128 v[174:177], v233 offset:20480
	ds_read_b128 v[178:181], v233 offset:21504
	ds_read_b128 v[182:185], v233 offset:22528
	ds_read_b128 v[186:189], v233 offset:23552
	global_load_lds_dwordx4 v250, s[16:17]
	s_nop 0
	s_mov_b32 m0, s55
	s_nop 0
	global_load_lds_dwordx4 v251, s[16:17]
	s_barrier
	s_waitcnt lgkmcnt(0)
	s_waitcnt lgkmcnt(0)
	s_nop 0
	v_mfma_f32_16x16x32_bf16 v[94:97], v[130:133], v[146:149], v[94:97]
	v_mfma_f32_16x16x32_bf16 v[90:93], v[138:141], v[146:149], v[90:93]
	v_mfma_f32_16x16x32_bf16 v[86:89], v[130:133], v[166:169], v[86:89]
	v_mfma_f32_16x16x32_bf16 v[82:85], v[138:141], v[166:169], v[82:85]
	v_mfma_f32_16x16x32_bf16 v[78:81], v[130:133], v[174:177], v[78:81]
	v_mfma_f32_16x16x32_bf16 v[74:77], v[138:141], v[174:177], v[74:77]
	v_mfma_f32_16x16x32_bf16 v[70:73], v[130:133], v[182:185], v[70:73]
	v_mfma_f32_16x16x32_bf16 v[66:69], v[138:141], v[182:185], v[66:69]
	v_mfma_f32_16x16x32_bf16 v[94:97], v[134:137], v[150:153], v[94:97]
	v_mfma_f32_16x16x32_bf16 v[90:93], v[142:145], v[150:153], v[90:93]
	v_mfma_f32_16x16x32_bf16 v[86:89], v[134:137], v[170:173], v[86:89]
	v_mfma_f32_16x16x32_bf16 v[82:85], v[142:145], v[170:173], v[82:85]
	v_mfma_f32_16x16x32_bf16 v[78:81], v[134:137], v[178:181], v[78:81]
	v_mfma_f32_16x16x32_bf16 v[74:77], v[142:145], v[178:181], v[74:77]
	v_mfma_f32_16x16x32_bf16 v[70:73], v[134:137], v[186:189], v[70:73]
	v_mfma_f32_16x16x32_bf16 v[66:69], v[142:145], v[186:189], v[66:69]
	s_barrier
	s_add_u32 s78, s2, 0x40000
	s_addc_u32 s79, s3, 0
	s_add_i32 s12, s13, s35
	v_lshl_add_u64 v[130:131], s[78:79], 0, v[0:1]
	s_mov_b32 m0, s12
	s_nop 0
	global_load_lds_dwordx4 v[130:131], off
	v_lshl_add_u64 v[130:131], s[78:79], 0, v[154:155]
	s_add_i32 m0, s12, 0x2000
	s_nop 0
	global_load_lds_dwordx4 v[130:131], off
	s_waitcnt vmcnt(6)
	s_barrier
	v_mfma_f32_16x16x32_bf16 v[30:33], v[190:193], v[146:149], v[30:33]
	v_mfma_f32_16x16x32_bf16 v[26:29], v[198:201], v[146:149], v[26:29]
	v_mfma_f32_16x16x32_bf16 v[22:25], v[190:193], v[166:169], v[22:25]
	v_mfma_f32_16x16x32_bf16 v[18:21], v[198:201], v[166:169], v[18:21]
	v_mfma_f32_16x16x32_bf16 v[14:17], v[190:193], v[174:177], v[14:17]
	v_mfma_f32_16x16x32_bf16 v[10:13], v[198:201], v[174:177], v[10:13]
	v_mfma_f32_16x16x32_bf16 v[6:9], v[190:193], v[182:185], v[6:9]
	v_mfma_f32_16x16x32_bf16 v[2:5], v[198:201], v[182:185], v[2:5]
	v_mfma_f32_16x16x32_bf16 v[30:33], v[194:197], v[150:153], v[30:33]
	v_mfma_f32_16x16x32_bf16 v[26:29], v[234:237], v[150:153], v[26:29]
	v_mfma_f32_16x16x32_bf16 v[22:25], v[194:197], v[170:173], v[22:25]
	v_mfma_f32_16x16x32_bf16 v[18:21], v[234:237], v[170:173], v[18:21]
	v_mfma_f32_16x16x32_bf16 v[14:17], v[194:197], v[178:181], v[14:17]
	v_mfma_f32_16x16x32_bf16 v[10:13], v[234:237], v[178:181], v[10:13]
	v_mfma_f32_16x16x32_bf16 v[6:9], v[194:197], v[186:189], v[6:9]
	v_mfma_f32_16x16x32_bf16 v[2:5], v[234:237], v[186:189], v[2:5]
	s_add_i32 s12, 0, 0x18000
	v_add_u32_e32 v142, s12, v227
	s_barrier
	ds_read_b128 v[130:133], v142
	ds_read_b128 v[134:137], v142 offset:1024
	ds_read_b128 v[138:141], v142 offset:2048
	ds_read_b128 v[142:145], v142 offset:3072
	s_add_u32 s16, s16, 0x40000
	s_addc_u32 s17, s17, 0
	s_mov_b32 m0, s58
	s_nop 0
	ds_read_b128 v[146:149], v233 offset:32768
	ds_read_b128 v[150:153], v233 offset:33792
	ds_read_b128 v[166:169], v233 offset:34816
	ds_read_b128 v[170:173], v233 offset:35840
	ds_read_b128 v[174:177], v233 offset:36864
	ds_read_b128 v[178:181], v233 offset:37888
	ds_read_b128 v[182:185], v233 offset:38912
	ds_read_b128 v[186:189], v233 offset:39936
	global_load_lds_dwordx4 v250, s[16:17]
	s_nop 0
	s_mov_b32 m0, s59
	s_nop 0
	global_load_lds_dwordx4 v251, s[16:17]
	s_waitcnt lgkmcnt(8)
	s_barrier
	s_waitcnt lgkmcnt(0)
	s_waitcnt lgkmcnt(0)
	v_mfma_f32_16x16x32_bf16 v[126:129], v[130:133], v[146:149], v[126:129]
	v_mfma_f32_16x16x32_bf16 v[122:125], v[138:141], v[146:149], v[122:125]
	v_mfma_f32_16x16x32_bf16 v[118:121], v[130:133], v[166:169], v[118:121]
	v_mfma_f32_16x16x32_bf16 v[114:117], v[138:141], v[166:169], v[114:117]
	v_mfma_f32_16x16x32_bf16 v[110:113], v[130:133], v[174:177], v[110:113]
	v_mfma_f32_16x16x32_bf16 v[106:109], v[138:141], v[174:177], v[106:109]
	v_mfma_f32_16x16x32_bf16 v[102:105], v[130:133], v[182:185], v[102:105]
	v_mfma_f32_16x16x32_bf16 v[98:101], v[138:141], v[182:185], v[98:101]
	v_mfma_f32_16x16x32_bf16 v[126:129], v[134:137], v[150:153], v[126:129]
	v_mfma_f32_16x16x32_bf16 v[122:125], v[142:145], v[150:153], v[122:125]
	v_mfma_f32_16x16x32_bf16 v[118:121], v[134:137], v[170:173], v[118:121]
	v_mfma_f32_16x16x32_bf16 v[114:117], v[142:145], v[170:173], v[114:117]
	v_mfma_f32_16x16x32_bf16 v[110:113], v[134:137], v[178:181], v[110:113]
	v_mfma_f32_16x16x32_bf16 v[106:109], v[142:145], v[178:181], v[106:109]
	v_mfma_f32_16x16x32_bf16 v[102:105], v[134:137], v[186:189], v[102:105]
	v_mfma_f32_16x16x32_bf16 v[98:101], v[142:145], v[186:189], v[98:101]
	s_barrier
	s_add_i32 s13, 0, 0x1c000
	s_add_i32 s12, s12, s35
	v_add_u32_e32 v234, s13, v227
	v_lshl_add_u64 v[242:243], v[242:243], 0, s[20:21]
	s_mov_b32 m0, s12
	ds_read_b128 v[190:193], v234
	ds_read_b128 v[194:197], v234 offset:1024
	ds_read_b128 v[198:201], v234 offset:2048
	ds_read_b128 v[234:237], v234 offset:3072
	global_load_lds_dwordx4 v[242:243], off
	v_lshl_add_u64 v[242:243], v[244:245], 0, s[20:21]
	s_add_i32 m0, s12, 0x2000
	s_nop 0
	global_load_lds_dwordx4 v[242:243], off
	s_barrier
	s_waitcnt lgkmcnt(0)
	s_waitcnt lgkmcnt(0)
	v_mfma_f32_16x16x32_bf16 v[62:65], v[190:193], v[146:149], v[62:65]
	v_mfma_f32_16x16x32_bf16 v[58:61], v[198:201], v[146:149], v[58:61]
	v_mfma_f32_16x16x32_bf16 v[54:57], v[190:193], v[166:169], v[54:57]
	v_mfma_f32_16x16x32_bf16 v[50:53], v[198:201], v[166:169], v[50:53]
	v_mfma_f32_16x16x32_bf16 v[46:49], v[190:193], v[174:177], v[46:49]
	v_mfma_f32_16x16x32_bf16 v[42:45], v[198:201], v[174:177], v[42:45]
	v_mfma_f32_16x16x32_bf16 v[38:41], v[190:193], v[182:185], v[38:41]
	v_mfma_f32_16x16x32_bf16 v[34:37], v[198:201], v[182:185], v[34:37]
	v_mfma_f32_16x16x32_bf16 v[62:65], v[194:197], v[150:153], v[62:65]
	v_mfma_f32_16x16x32_bf16 v[58:61], v[234:237], v[150:153], v[58:61]
	v_mfma_f32_16x16x32_bf16 v[54:57], v[194:197], v[170:173], v[54:57]
	v_mfma_f32_16x16x32_bf16 v[50:53], v[234:237], v[170:173], v[50:53]
	v_mfma_f32_16x16x32_bf16 v[46:49], v[194:197], v[178:181], v[46:49]
	v_mfma_f32_16x16x32_bf16 v[42:45], v[234:237], v[178:181], v[42:45]
	v_mfma_f32_16x16x32_bf16 v[38:41], v[194:197], v[186:189], v[38:41]
	v_mfma_f32_16x16x32_bf16 v[34:37], v[234:237], v[186:189], v[34:37]
	s_mov_b32 m0, s96
	s_add_u32 s78, s16, 0xfffc0080
	s_addc_u32 s79, s17, -1
	s_barrier
	ds_read_b128 v[146:149], v233 offset:49152
	ds_read_b128 v[150:153], v233 offset:50176
	ds_read_b128 v[166:169], v233 offset:51200
	ds_read_b128 v[170:173], v233 offset:52224
	ds_read_b128 v[174:177], v233 offset:53248
	ds_read_b128 v[178:181], v233 offset:54272
	ds_read_b128 v[182:185], v233 offset:55296
	ds_read_b128 v[186:189], v233 offset:56320
	global_load_lds_dwordx4 v250, s[78:79]
	s_nop 0
	s_mov_b32 m0, s97
	s_nop 0
	global_load_lds_dwordx4 v251, s[78:79]
	s_barrier
	s_waitcnt lgkmcnt(0)
	s_waitcnt lgkmcnt(0)
	s_nop 0
	v_mfma_f32_16x16x32_bf16 v[94:97], v[130:133], v[146:149], v[94:97]
	v_mfma_f32_16x16x32_bf16 v[90:93], v[138:141], v[146:149], v[90:93]
	v_mfma_f32_16x16x32_bf16 v[86:89], v[130:133], v[166:169], v[86:89]
	v_mfma_f32_16x16x32_bf16 v[82:85], v[138:141], v[166:169], v[82:85]
	v_mfma_f32_16x16x32_bf16 v[78:81], v[130:133], v[174:177], v[78:81]
	v_mfma_f32_16x16x32_bf16 v[74:77], v[138:141], v[174:177], v[74:77]
	v_mfma_f32_16x16x32_bf16 v[70:73], v[130:133], v[182:185], v[70:73]
	v_mfma_f32_16x16x32_bf16 v[66:69], v[138:141], v[182:185], v[66:69]
	v_mfma_f32_16x16x32_bf16 v[94:97], v[134:137], v[150:153], v[94:97]
	v_mfma_f32_16x16x32_bf16 v[90:93], v[142:145], v[150:153], v[90:93]
	v_mfma_f32_16x16x32_bf16 v[86:89], v[134:137], v[170:173], v[86:89]
	v_mfma_f32_16x16x32_bf16 v[82:85], v[142:145], v[170:173], v[82:85]
	v_mfma_f32_16x16x32_bf16 v[78:81], v[134:137], v[178:181], v[78:81]
	v_mfma_f32_16x16x32_bf16 v[74:77], v[142:145], v[178:181], v[74:77]
	v_mfma_f32_16x16x32_bf16 v[70:73], v[134:137], v[186:189], v[70:73]
	v_mfma_f32_16x16x32_bf16 v[66:69], v[142:145], v[186:189], v[66:69]
	s_barrier
	s_add_u32 s2, s2, 0x40080
	s_addc_u32 s3, s3, 0
	s_add_i32 s12, s13, s35
	v_lshl_add_u64 v[130:131], s[2:3], 0, v[0:1]
	s_mov_b32 m0, s12
	s_nop 0
	global_load_lds_dwordx4 v[130:131], off
	v_lshl_add_u64 v[130:131], s[2:3], 0, v[154:155]
	s_add_i32 m0, s12, 0x2000
	s_nop 0
	global_load_lds_dwordx4 v[130:131], off
	s_waitcnt vmcnt(6)
	s_barrier
	v_mfma_f32_16x16x32_bf16 v[30:33], v[190:193], v[146:149], v[30:33]
	v_mfma_f32_16x16x32_bf16 v[26:29], v[198:201], v[146:149], v[26:29]
	v_mfma_f32_16x16x32_bf16 v[22:25], v[190:193], v[166:169], v[22:25]
	v_mfma_f32_16x16x32_bf16 v[18:21], v[198:201], v[166:169], v[18:21]
	v_mfma_f32_16x16x32_bf16 v[14:17], v[190:193], v[174:177], v[14:17]
	v_mfma_f32_16x16x32_bf16 v[10:13], v[198:201], v[174:177], v[10:13]
	v_mfma_f32_16x16x32_bf16 v[6:9], v[190:193], v[182:185], v[6:9]
	v_mfma_f32_16x16x32_bf16 v[2:5], v[198:201], v[182:185], v[2:5]
	v_mfma_f32_16x16x32_bf16 v[30:33], v[194:197], v[150:153], v[30:33]
	v_mfma_f32_16x16x32_bf16 v[26:29], v[234:237], v[150:153], v[26:29]
	v_mfma_f32_16x16x32_bf16 v[22:25], v[194:197], v[170:173], v[22:25]
	v_mfma_f32_16x16x32_bf16 v[18:21], v[234:237], v[170:173], v[18:21]
	v_mfma_f32_16x16x32_bf16 v[14:17], v[194:197], v[178:181], v[14:17]
	v_mfma_f32_16x16x32_bf16 v[10:13], v[234:237], v[178:181], v[10:13]
	v_mfma_f32_16x16x32_bf16 v[6:9], v[194:197], v[186:189], v[6:9]
	v_mfma_f32_16x16x32_bf16 v[2:5], v[234:237], v[186:189], v[2:5]
	s_add_i32 s47, s47, 2
	s_add_u32 s0, s0, 0x100
	s_addc_u32 s1, s1, 0
	s_add_u32 s45, s45, 0x100
	s_addc_u32 s46, s46, 0
	s_cmp_gt_u32 s47, 13
	s_barrier
	s_cbranch_scc0 .LBB0_366
.Lpeel_x_366:
.Lq_epi:
	s_lshl_b32 s2, s42, 8
	s_add_i32 s2, s2, s92
	s_lshl_b32 s3, s14, 8
	s_or_b32 s3, s3, s93
	v_readlane_b32 s44, v255, 8
	v_readlane_b32 s45, v255, 9
	s_add_u32 s60, s8, 0xc404000
	s_addc_u32 s61, s9, 0
	v_lshl_add_u32 v166, v226, 2, s2
	s_cmp_lt_i32 s42, 64
	s_cselect_b32 s47, 1, 0
	v_mul_lo_u32 v167, v166, s57
	s_nop 0
	v_lshl_add_u32 v167, v228, 1, v167
	s_and_b32 s12, s98, 5
	s_cbranch_scc0 .Lip0_end
	s_cmpk_gt_i32 s3, 0xb7f
	s_cbranch_scc1 .Lip0_end
	s_lshl_b32 s12, s3, 1
	v_add_u32_e32 v169, s12, v167
	s_add_i32 s0, s3, 0xfffffc00
	s_add_i32 s1, s3, 0xfffff780
	s_min_u32 s12, s0, s1
	s_cmpk_lt_u32 s12, 0x180
	s_cbranch_scc1 .Lip0_V
	s_add_i32 s12, s3, 0xfffffa80
	s_cmpk_lt_u32 s12, 0x300
	s_cbranch_scc1 .Lip0_R
	s_add_i32 s12, s3, 0xffffff00
	s_cmpk_lt_u32 s12, 0x180
	s_cbranch_scc0 .Lip0_nonq
	v_mul_f32_e32 v126, 0x3e38aa3b, v126
	v_mul_f32_e32 v127, 0x3e38aa3b, v127
	v_mul_f32_e32 v128, 0x3e38aa3b, v128
	v_mul_f32_e32 v129, 0x3e38aa3b, v129
	v_mul_f32_e32 v122, 0x3e38aa3b, v122
	v_mul_f32_e32 v123, 0x3e38aa3b, v123
	v_mul_f32_e32 v124, 0x3e38aa3b, v124
	v_mul_f32_e32 v125, 0x3e38aa3b, v125
	v_mul_f32_e32 v118, 0x3e38aa3b, v118
	v_mul_f32_e32 v119, 0x3e38aa3b, v119
	v_mul_f32_e32 v120, 0x3e38aa3b, v120
	v_mul_f32_e32 v121, 0x3e38aa3b, v121
	v_mul_f32_e32 v114, 0x3e38aa3b, v114
	v_mul_f32_e32 v115, 0x3e38aa3b, v115
	v_mul_f32_e32 v116, 0x3e38aa3b, v116
	v_mul_f32_e32 v117, 0x3e38aa3b, v117
	v_mul_f32_e32 v110, 0x3e38aa3b, v110
	v_mul_f32_e32 v111, 0x3e38aa3b, v111
	v_mul_f32_e32 v112, 0x3e38aa3b, v112
	v_mul_f32_e32 v113, 0x3e38aa3b, v113
	v_mul_f32_e32 v106, 0x3e38aa3b, v106
	v_mul_f32_e32 v107, 0x3e38aa3b, v107
	v_mul_f32_e32 v108, 0x3e38aa3b, v108
	v_mul_f32_e32 v109, 0x3e38aa3b, v109
	v_mul_f32_e32 v102, 0x3e38aa3b, v102
	v_mul_f32_e32 v103, 0x3e38aa3b, v103
	v_mul_f32_e32 v104, 0x3e38aa3b, v104
	v_mul_f32_e32 v105, 0x3e38aa3b, v105
	v_mul_f32_e32 v98, 0x3e38aa3b, v98
	v_mul_f32_e32 v99, 0x3e38aa3b, v99
	v_mul_f32_e32 v100, 0x3e38aa3b, v100
	v_mul_f32_e32 v101, 0x3e38aa3b, v101
	v_mul_f32_e32 v94, 0x3e38aa3b, v94
	v_mul_f32_e32 v95, 0x3e38aa3b, v95
	v_mul_f32_e32 v96, 0x3e38aa3b, v96
	v_mul_f32_e32 v97, 0x3e38aa3b, v97
	v_mul_f32_e32 v90, 0x3e38aa3b, v90
	v_mul_f32_e32 v91, 0x3e38aa3b, v91
	v_mul_f32_e32 v92, 0x3e38aa3b, v92
	v_mul_f32_e32 v93, 0x3e38aa3b, v93
	v_mul_f32_e32 v86, 0x3e38aa3b, v86
	v_mul_f32_e32 v87, 0x3e38aa3b, v87
	v_mul_f32_e32 v88, 0x3e38aa3b, v88
	v_mul_f32_e32 v89, 0x3e38aa3b, v89
	v_mul_f32_e32 v82, 0x3e38aa3b, v82
	v_mul_f32_e32 v83, 0x3e38aa3b, v83
	v_mul_f32_e32 v84, 0x3e38aa3b, v84
	v_mul_f32_e32 v85, 0x3e38aa3b, v85
	v_mul_f32_e32 v78, 0x3e38aa3b, v78
	v_mul_f32_e32 v79, 0x3e38aa3b, v79
	v_mul_f32_e32 v80, 0x3e38aa3b, v80
	v_mul_f32_e32 v81, 0x3e38aa3b, v81
	v_mul_f32_e32 v74, 0x3e38aa3b, v74
	v_mul_f32_e32 v75, 0x3e38aa3b, v75
	v_mul_f32_e32 v76, 0x3e38aa3b, v76
	v_mul_f32_e32 v77, 0x3e38aa3b, v77
	v_mul_f32_e32 v70, 0x3e38aa3b, v70
	v_mul_f32_e32 v71, 0x3e38aa3b, v71
	v_mul_f32_e32 v72, 0x3e38aa3b, v72
	v_mul_f32_e32 v73, 0x3e38aa3b, v73
	v_mul_f32_e32 v66, 0x3e38aa3b, v66
	v_mul_f32_e32 v67, 0x3e38aa3b, v67
	v_mul_f32_e32 v68, 0x3e38aa3b, v68
	v_mul_f32_e32 v69, 0x3e38aa3b, v69

.Lq_unit:
	v_mov_b32_e32 v3, v2
	v_mov_b64_e32 v[4:5], v[2:3]
	v_mov_b64_e32 v[6:7], v[2:3]
	v_mov_b64_e32 v[8:9], v[2:3]
	v_mov_b64_e32 v[10:11], v[2:3]
	v_mov_b64_e32 v[12:13], v[2:3]
	v_mov_b64_e32 v[14:15], v[2:3]
	v_mov_b64_e32 v[16:17], v[2:3]
	v_mov_b64_e32 v[18:19], v[2:3]
	v_mov_b64_e32 v[20:21], v[2:3]
	v_mov_b64_e32 v[22:23], v[2:3]
	v_mov_b64_e32 v[24:25], v[2:3]
	v_mov_b64_e32 v[26:27], v[2:3]
	v_mov_b64_e32 v[28:29], v[2:3]
	v_mov_b64_e32 v[30:31], v[2:3]
	v_mov_b64_e32 v[32:33], v[2:3]
	v_mov_b64_e32 v[66:67], v[2:3]
	v_mov_b64_e32 v[68:69], v[2:3]
	v_mov_b64_e32 v[70:71], v[2:3]
	v_mov_b64_e32 v[72:73], v[2:3]
	v_mov_b64_e32 v[74:75], v[2:3]
	v_mov_b64_e32 v[76:77], v[2:3]
	v_mov_b64_e32 v[78:79], v[2:3]
	v_mov_b64_e32 v[80:81], v[2:3]
	v_mov_b64_e32 v[82:83], v[2:3]
	v_mov_b64_e32 v[84:85], v[2:3]
	v_mov_b64_e32 v[86:87], v[2:3]
	v_mov_b64_e32 v[88:89], v[2:3]
	v_mov_b64_e32 v[90:91], v[2:3]
	v_mov_b64_e32 v[92:93], v[2:3]
	v_mov_b64_e32 v[94:95], v[2:3]
	v_mov_b64_e32 v[96:97], v[2:3]
	v_mov_b64_e32 v[34:35], v[2:3]
	v_mov_b64_e32 v[36:37], v[2:3]
	v_mov_b64_e32 v[38:39], v[2:3]
	v_mov_b64_e32 v[40:41], v[2:3]
	v_mov_b64_e32 v[42:43], v[2:3]
	v_mov_b64_e32 v[44:45], v[2:3]
	v_mov_b64_e32 v[46:47], v[2:3]
	v_mov_b64_e32 v[48:49], v[2:3]
	v_mov_b64_e32 v[50:51], v[2:3]
	v_mov_b64_e32 v[52:53], v[2:3]
	v_mov_b64_e32 v[54:55], v[2:3]
	v_mov_b64_e32 v[56:57], v[2:3]
	v_mov_b64_e32 v[58:59], v[2:3]
	v_mov_b64_e32 v[60:61], v[2:3]
	v_mov_b64_e32 v[62:63], v[2:3]
	v_mov_b64_e32 v[64:65], v[2:3]
	v_mov_b64_e32 v[98:99], v[2:3]
	v_mov_b64_e32 v[100:101], v[2:3]
	v_mov_b64_e32 v[102:103], v[2:3]
	v_mov_b64_e32 v[104:105], v[2:3]
	v_mov_b64_e32 v[106:107], v[2:3]
	v_mov_b64_e32 v[108:109], v[2:3]
	v_mov_b64_e32 v[110:111], v[2:3]
	v_mov_b64_e32 v[112:113], v[2:3]
	v_mov_b64_e32 v[114:115], v[2:3]
	v_mov_b64_e32 v[116:117], v[2:3]
	v_mov_b64_e32 v[118:119], v[2:3]
	v_mov_b64_e32 v[120:121], v[2:3]
	v_mov_b64_e32 v[122:123], v[2:3]
	v_mov_b64_e32 v[124:125], v[2:3]
	v_mov_b64_e32 v[126:127], v[2:3]
	v_mov_b64_e32 v[128:129], v[2:3]
	s_ff1_i32_b32 s2, s98
	s_lshr_b32 s3, s2, 1
	s_and_b32 s2, s2, 1
	s_lshl_b32 s12, s3, 14
	s_xor_b32 s13, s12, 0x4000
	v_add_u32_e32 v190, s12, v233
	v_add_u32_e32 v192, s13, v233
	s_add_i32 s44, s54, s12
	s_add_i32 s46, s54, s13
	s_lshl_b32 s12, s2, 14
	s_xor_b32 s13, s12, 0x4000
	s_add_i32 s12, s12, 0x10000
	s_add_i32 s13, s13, 0x10000
	v_add_u32_e32 v191, s12, v227
	v_add_u32_e32 v193, s13, v227
	s_add_i32 s45, s54, s12
	s_add_i32 s47, s54, s13
	s_lshl_b32 s12, s3, 18
	s_lshl_b32 s13, s2, 18
	s_add_u32 s0, s0, 0xfffbff80
	s_addc_u32 s1, s1, -1
	s_add_u32 s0, s0, s12
	s_addc_u32 s1, s1, 0
	s_add_u32 s0, s0, 0x100
	s_addc_u32 s1, s1, 0
	s_add_u32 s16, s16, s13
	s_addc_u32 s17, s17, 0
	s_add_u32 s16, s16, 0x100
	s_addc_u32 s17, s17, 0
	s_add_u32 s2, s0, 0xffffff80
	s_addc_u32 s3, s1, -1
	s_add_i32 m0, s44, 0x8000
	s_nop 0
	global_load_lds_dwordx4 v250, s[2:3]
	s_add_i32 m0, s44, 0xa000
	s_nop 0
	global_load_lds_dwordx4 v251, s[2:3]
	s_waitcnt vmcnt(0)
	s_cmpk_gt_u32 s22, 0xff
	s_cbranch_scc1 .Lq_aligned
	s_barrier
